# P4 epilogue sum-of-squares lane exchanges also via v_permlane16/32_swap (with the 2-state pad after the 128-bit store)
# speedup vs baseline: 1.0084x; 1.0015x over previous
; __device__ __forceinline__ unsigned cvt_pk_bf16(float lo, float hi) { const f32x2_t v = {lo, hi}; const bf16x2_t b = __builtin_convertvector(v, bf16x2_t); return __builtin_bit_cast(unsigned, b); }
;     __device__ __forceinline__ void operator()(f32x4 (&acc)[2][2][4][2], const Unit& u, int wr, int wc, int fr, int fq) const {
;         const int c0 = u.pn * BM + wc * 64 + 8 * fq;
;         const float* xb = (u.pm < MP / BM) ? xp : (xs - (size_t)MP * DM);
; #pragma unroll
;         for (int ai = 0; ai < 2; ++ai) {
;             f32x4 xv[4][2][2];
; #pragma unroll
;             for (int m = 0; m < 4; ++m) { const float* xrow = xb + (size_t)EPI_ROWS(ai, m) * DM + c0;
; #pragma unroll
;                 for (int bj = 0; bj < 2; ++bj) { xv[m][bj][0] = __builtin_nontemporal_load((const f32x4*)(xrow + 32 * bj)); xv[m][bj][1] = __builtin_nontemporal_load((const f32x4*)(xrow + 32 * bj + 4)); } }
;             asm volatile("" ::: "memory");
; #pragma unroll
;             for (int m = 0; m < 4; ++m) {
;                 const int r = EPI_ROWS(ai, m);
;                 float ss = 0.f;
; #pragma unroll
;                 for (int bj = 0; bj < 2; ++bj) {
;                     const f32x4 h0 = acc[ai][bj][m][0] + xv[m][bj][0], h1 = acc[ai][bj][m][1] + xv[m][bj][1];
;                     ss += (h0[0] * h0[0] + h0[1] * h0[1]) + (h0[2] * h0[2] + h0[3] * h0[3]) + (h1[0] * h1[0] + h1[1] * h1[1]) + (h1[2] * h1[2] + h1[3] * h1[3]);
;                     u32x4 w; w.x = cvt_pk_bf16(h0[0], h0[1]); w.y = cvt_pk_bf16(h0[2], h0[3]); w.z = cvt_pk_bf16(h1[0], h1[1]); w.w = cvt_pk_bf16(h1[2], h1[3]);
;                     *(u32x4*)(HP + (size_t)r * LDHP + c0 + 32 * bj) = w;
;                 }
;                 ss += __shfl_xor(ss, 16); ss += __shfl_xor(ss, 32);
;                 if (fq == 0) SS[(size_t)r * 16 + u.pn * 4 + wc] = ss;
;             }
.LBB0_902:
	s_cmpk_lt_i32 s74, 0x80
	v_lshl_or_b32 v204, s72, 8, v217
	s_cselect_b32 s0, s65, s34
	s_cselect_b32 s2, s64, s31
	v_lshl_add_u32 v208, s74, 8, v1
	v_mov_b32_e32 v130, s2
	v_mov_b32_e32 v131, s0
	v_ashrrev_i32_e32 v205, 31, v204
	v_ashrrev_i32_e32 v209, 31, v208
	v_lshl_add_u64 v[206:207], v[204:205], 2, v[130:131]
	v_lshlrev_b64 v[130:131], 12, v[208:209]
	v_lshl_add_u64 v[130:131], v[206:207], 0, v[130:131]
	global_load_dwordx4 v[224:227], v[130:131], off offset:16 nt
	global_load_dwordx4 v[228:231], v[130:131], off nt
	global_load_dwordx4 v[178:181], v[130:131], off offset:144 nt
	global_load_dwordx4 v[182:185], v[130:131], off offset:128 nt
	v_or_b32_e32 v214, 16, v208
	v_ashrrev_i32_e32 v215, 31, v214
	v_lshlrev_b64 v[130:131], 12, v[214:215]
	v_or_b32_e32 v212, 32, v208
	v_lshl_add_u64 v[130:131], v[206:207], 0, v[130:131]
	v_ashrrev_i32_e32 v213, 31, v212
	global_load_dwordx4 v[170:173], v[130:131], off offset:16 nt
	global_load_dwordx4 v[174:177], v[130:131], off nt
	global_load_dwordx4 v[162:165], v[130:131], off offset:144 nt
	global_load_dwordx4 v[166:169], v[130:131], off offset:128 nt
	v_lshlrev_b64 v[130:131], 12, v[212:213]
	v_or_b32_e32 v210, 48, v208
	v_lshl_add_u64 v[130:131], v[206:207], 0, v[130:131]
	v_ashrrev_i32_e32 v211, 31, v210
	global_load_dwordx4 v[154:157], v[130:131], off offset:16 nt
	global_load_dwordx4 v[158:161], v[130:131], off nt
	global_load_dwordx4 v[138:141], v[130:131], off offset:144 nt
	global_load_dwordx4 v[146:149], v[130:131], off offset:128 nt
	v_lshlrev_b64 v[130:131], 12, v[210:211]
	v_lshl_add_u64 v[134:135], v[206:207], 0, v[130:131]
	global_load_dwordx4 v[142:145], v[134:135], off offset:16 nt
	global_load_dwordx4 v[150:153], v[134:135], off nt
	global_load_dwordx4 v[130:133], v[134:135], off offset:144 nt
	s_nop 0
	global_load_dwordx4 v[134:137], v[134:135], off offset:128 nt
	v_and_b32_e32 v223, 64, v221
	v_xor_b32_e32 v222, 16, v221
	v_add_u32_e32 v223, 64, v223
	v_cmp_lt_i32_e32 vcc, v222, v223
	v_xor_b32_e32 v232, 32, v221
	s_lshl_b32 s66, s72, 2
	v_cndmask_b32_e32 v222, v221, v222, vcc
	v_lshlrev_b32_e32 v222, 2, v222
	v_cmp_lt_i32_e32 vcc, v232, v223
	s_ashr_i32 s67, s66, 31
	s_waitcnt vmcnt(15)
	v_pk_add_f32 v[226:227], v[124:125], v[226:227]
	s_waitcnt vmcnt(14)
	v_pk_add_f32 v[128:129], v[128:129], v[230:231]
	v_pk_add_f32 v[126:127], v[126:127], v[228:229]
	v_pk_add_f32 v[124:125], v[122:123], v[224:225]
	v_mul_f32_e32 v122, v127, v127
	v_mul_f32_e32 v123, v129, v129
	v_fmac_f32_e32 v122, v126, v126
	v_fmac_f32_e32 v123, v128, v128
	v_add_f32_e32 v122, v122, v123
	v_mul_f32_e32 v123, v125, v125
	v_fmac_f32_e32 v123, v124, v124
	v_add_f32_e32 v122, v122, v123
	v_mul_f32_e32 v123, v227, v227
	v_fmac_f32_e32 v123, v226, v226
	v_add_f32_e32 v224, v123, v122
	v_cvt_pk_bf16_f32 v122, v126, v127
	v_mov_b64_e32 v[126:127], s[82:83]
	v_mad_i64_i32 v[126:127], s[2:3], v208, s54, v[126:127]
	v_cvt_pk_bf16_f32 v123, v128, v129
	v_cvt_pk_bf16_f32 v124, v124, v125
	v_cvt_pk_bf16_f32 v125, v226, v227
	v_lshl_add_u64 v[126:127], v[204:205], 1, v[126:127]
	s_waitcnt vmcnt(12)
	v_pk_add_f32 v[120:121], v[120:121], v[184:185]
	v_pk_add_f32 v[118:119], v[118:119], v[182:183]
	global_store_dwordx4 v[126:127], v[122:125], off
	v_cndmask_b32_e32 v223, v221, v232, vcc
	v_lshlrev_b32_e32 v223, 2, v223
	v_pk_add_f32 v[122:123], v[116:117], v[180:181]
	v_pk_add_f32 v[116:117], v[114:115], v[178:179]
	v_mul_f32_e32 v114, v119, v119
	v_mul_f32_e32 v115, v121, v121
	v_fmac_f32_e32 v114, v118, v118
	v_fmac_f32_e32 v115, v120, v120
	v_add_f32_e32 v114, v114, v115
	v_mul_f32_e32 v115, v117, v117
	v_fmac_f32_e32 v115, v116, v116
	v_add_f32_e32 v114, v114, v115
	v_mul_f32_e32 v115, v123, v123
	v_fmac_f32_e32 v115, v122, v122
	v_add_f32_e32 v114, v115, v114
	v_add_f32_e32 v124, v224, v114
	v_cvt_pk_bf16_f32 v114, v118, v119
	v_cvt_pk_bf16_f32 v115, v120, v121
	v_cvt_pk_bf16_f32 v116, v116, v117
	v_cvt_pk_bf16_f32 v117, v122, v123
	global_store_dwordx4 v[126:127], v[114:117], off offset:64
	s_nop 1
	v_mov_b32_e32 v114, v124
	s_nop 1
	v_permlane16_swap_b32_e32 v114, v124
	s_waitcnt lgkmcnt(0)
	v_add_f32_e32 v114, v124, v114
	s_nop 1
	v_mov_b32_e32 v115, v114
	s_nop 1
	v_permlane32_swap_b32_e32 v115, v114
	s_and_saveexec_b64 s[18:19], s[40:41]
	s_cbranch_execz .LBB0_904
	v_lshlrev_b64 v[116:117], 6, v[208:209]
	v_lshl_add_u64 v[116:117], s[8:9], 0, v[116:117]
	v_lshl_add_u64 v[116:117], s[66:67], 2, v[116:117]
	s_lshl_b32 s0, s30, 2
	v_lshl_add_u64 v[116:117], v[116:117], 0, s[0:1]
	s_waitcnt lgkmcnt(0)
	v_add_f32_e32 v114, v114, v115
	global_store_dword v[116:117], v114, off
; __device__ __forceinline__ unsigned cvt_pk_bf16(float lo, float hi) { const f32x2_t v = {lo, hi}; const bf16x2_t b = __builtin_convertvector(v, bf16x2_t); return __builtin_bit_cast(unsigned, b); }
;     __device__ __forceinline__ void operator()(f32x4 (&acc)[2][2][4][2], const Unit& u, int wr, int wc, int fr, int fq) const {
;     ...
;             for (int m = 0; m < 4; ++m) {
;                 const int r = EPI_ROWS(ai, m);
;                 float ss = 0.f;
; #pragma unroll
;                 for (int bj = 0; bj < 2; ++bj) {
;                     const f32x4 h0 = acc[ai][bj][m][0] + xv[m][bj][0], h1 = acc[ai][bj][m][1] + xv[m][bj][1];
;                     ss += (h0[0] * h0[0] + h0[1] * h0[1]) + (h0[2] * h0[2] + h0[3] * h0[3]) + (h1[0] * h1[0] + h1[1] * h1[1]) + (h1[2] * h1[2] + h1[3] * h1[3]);
;                     u32x4 w; w.x = cvt_pk_bf16(h0[0], h0[1]); w.y = cvt_pk_bf16(h0[2], h0[3]); w.z = cvt_pk_bf16(h1[0], h1[1]); w.w = cvt_pk_bf16(h1[2], h1[3]);
;                     *(u32x4*)(HP + (size_t)r * LDHP + c0 + 32 * bj) = w;
;                 }
;                 ss += __shfl_xor(ss, 16); ss += __shfl_xor(ss, 32);
;                 if (fq == 0) SS[(size_t)r * 16 + u.pn * 4 + wc] = ss;
;             }
.LBB0_904:
	s_or_b64 exec, exec, s[18:19]
	s_waitcnt vmcnt(12)
	v_pk_add_f32 v[112:113], v[112:113], v[176:177]
	v_pk_add_f32 v[110:111], v[110:111], v[174:175]
	s_waitcnt lgkmcnt(0)
	v_pk_add_f32 v[114:115], v[108:109], v[172:173]
	v_pk_add_f32 v[108:109], v[106:107], v[170:171]
	v_mul_f32_e32 v106, v111, v111
	v_mul_f32_e32 v107, v113, v113
	v_fmac_f32_e32 v106, v110, v110
	v_fmac_f32_e32 v107, v112, v112
	v_add_f32_e32 v106, v106, v107
	v_mul_f32_e32 v107, v109, v109
	v_fmac_f32_e32 v107, v108, v108
	v_add_f32_e32 v106, v106, v107
	v_mul_f32_e32 v107, v115, v115
	s_waitcnt vmcnt(10)
	v_pk_add_f32 v[104:105], v[104:105], v[168:169]
	v_pk_add_f32 v[102:103], v[102:103], v[166:167]
	v_fmac_f32_e32 v107, v114, v114
	v_cvt_pk_bf16_f32 v108, v108, v109
	v_cvt_pk_bf16_f32 v109, v114, v115
	v_pk_add_f32 v[114:115], v[98:99], v[162:163]
	v_mul_f32_e32 v98, v103, v103
	v_mul_f32_e32 v99, v105, v105
	v_fmac_f32_e32 v98, v102, v102
	v_fmac_f32_e32 v99, v104, v104
	v_add_f32_e32 v98, v98, v99
	v_mul_f32_e32 v99, v115, v115
	v_add_f32_e32 v116, v107, v106
	v_cvt_pk_bf16_f32 v107, v112, v113
	v_pk_add_f32 v[112:113], v[100:101], v[164:165]
	v_fmac_f32_e32 v99, v114, v114
	v_add_f32_e32 v98, v98, v99
	v_mul_f32_e32 v99, v113, v113
	v_fmac_f32_e32 v99, v112, v112
	v_add_f32_e32 v98, v99, v98
	v_add_f32_e32 v101, v116, v98
	s_nop 1
	v_mov_b32_e32 v116, v101
	s_nop 1
	v_permlane16_swap_b32_e32 v116, v101
	v_cvt_pk_bf16_f32 v106, v110, v111
	v_mov_b64_e32 v[110:111], s[82:83]
	v_mad_i64_i32 v[98:99], s[2:3], v214, s54, v[110:111]
	v_lshl_add_u64 v[110:111], v[204:205], 1, v[98:99]
	s_waitcnt lgkmcnt(0)
	v_add_f32_e32 v98, v101, v116
	s_nop 1
	v_mov_b32_e32 v99, v98
	s_nop 1
	v_permlane32_swap_b32_e32 v99, v98
	v_cvt_pk_bf16_f32 v100, v102, v103
	v_cvt_pk_bf16_f32 v101, v104, v105
	v_cvt_pk_bf16_f32 v102, v114, v115
	v_cvt_pk_bf16_f32 v103, v112, v113
	global_store_dwordx4 v[110:111], v[106:109], off
	global_store_dwordx4 v[110:111], v[100:103], off offset:64
	s_and_saveexec_b64 s[18:19], s[40:41]
	s_cbranch_execz .LBB0_906
	v_lshlrev_b64 v[100:101], 6, v[214:215]
	v_lshl_add_u64 v[100:101], s[8:9], 0, v[100:101]
	v_lshl_add_u64 v[100:101], s[66:67], 2, v[100:101]
	s_lshl_b32 s0, s30, 2
	v_lshl_add_u64 v[100:101], v[100:101], 0, s[0:1]
	s_waitcnt lgkmcnt(0)
	v_add_f32_e32 v98, v98, v99
	global_store_dword v[100:101], v98, off
.LBB0_906:
	s_or_b64 exec, exec, s[18:19]
	s_waitcnt vmcnt(10)
	v_pk_add_f32 v[96:97], v[96:97], v[160:161]
	v_pk_add_f32 v[94:95], v[94:95], v[158:159]
	s_waitcnt lgkmcnt(0)
	v_pk_add_f32 v[98:99], v[92:93], v[156:157]
	v_pk_add_f32 v[92:93], v[90:91], v[154:155]
	v_mul_f32_e32 v90, v95, v95
	v_mul_f32_e32 v91, v97, v97
	v_fmac_f32_e32 v90, v94, v94
	v_fmac_f32_e32 v91, v96, v96
	v_add_f32_e32 v90, v90, v91
	v_mul_f32_e32 v91, v93, v93
	v_fmac_f32_e32 v91, v92, v92
	v_add_f32_e32 v90, v90, v91
	v_mul_f32_e32 v91, v99, v99
	s_waitcnt vmcnt(8)
	v_pk_add_f32 v[88:89], v[88:89], v[148:149]
	v_pk_add_f32 v[86:87], v[86:87], v[146:147]
	v_fmac_f32_e32 v91, v98, v98
	v_cvt_pk_bf16_f32 v92, v92, v93
	v_cvt_pk_bf16_f32 v93, v98, v99
	v_pk_add_f32 v[98:99], v[82:83], v[138:139]
	v_mul_f32_e32 v82, v87, v87
	v_mul_f32_e32 v83, v89, v89
	v_fmac_f32_e32 v82, v86, v86
	v_fmac_f32_e32 v83, v88, v88
	v_add_f32_e32 v82, v82, v83
	v_mul_f32_e32 v83, v99, v99
	v_add_f32_e32 v100, v91, v90
	v_cvt_pk_bf16_f32 v91, v96, v97
	v_pk_add_f32 v[96:97], v[84:85], v[140:141]
	v_fmac_f32_e32 v83, v98, v98
	v_add_f32_e32 v82, v82, v83
	v_mul_f32_e32 v83, v97, v97
	v_fmac_f32_e32 v83, v96, v96
	v_add_f32_e32 v82, v83, v82
	v_add_f32_e32 v85, v100, v82
	s_nop 1
	v_mov_b32_e32 v100, v85
	s_nop 1
	v_permlane16_swap_b32_e32 v100, v85
	v_cvt_pk_bf16_f32 v90, v94, v95
	v_mov_b64_e32 v[94:95], s[82:83]
	v_mad_i64_i32 v[82:83], s[2:3], v212, s54, v[94:95]
	v_lshl_add_u64 v[94:95], v[204:205], 1, v[82:83]
	s_waitcnt lgkmcnt(0)
	v_add_f32_e32 v82, v85, v100
	s_nop 1
	v_mov_b32_e32 v83, v82
	s_nop 1
	v_permlane32_swap_b32_e32 v83, v82
	v_cvt_pk_bf16_f32 v84, v86, v87
	v_cvt_pk_bf16_f32 v85, v88, v89
	v_cvt_pk_bf16_f32 v86, v98, v99
	v_cvt_pk_bf16_f32 v87, v96, v97
	global_store_dwordx4 v[94:95], v[90:93], off
	global_store_dwordx4 v[94:95], v[84:87], off offset:64
	s_and_saveexec_b64 s[18:19], s[40:41]
	s_cbranch_execz .LBB0_908
	v_lshlrev_b64 v[84:85], 6, v[212:213]
	v_lshl_add_u64 v[84:85], s[8:9], 0, v[84:85]
	v_lshl_add_u64 v[84:85], s[66:67], 2, v[84:85]
	s_lshl_b32 s0, s30, 2
	v_lshl_add_u64 v[84:85], v[84:85], 0, s[0:1]
	s_waitcnt lgkmcnt(0)
	v_add_f32_e32 v82, v82, v83
	global_store_dword v[84:85], v82, off
; __device__ __forceinline__ unsigned cvt_pk_bf16(float lo, float hi) { const f32x2_t v = {lo, hi}; const bf16x2_t b = __builtin_convertvector(v, bf16x2_t); return __builtin_bit_cast(unsigned, b); }
;     __device__ __forceinline__ void operator()(f32x4 (&acc)[2][2][4][2], const Unit& u, int wr, int wc, int fr, int fq) const {
;     ...
;             for (int m = 0; m < 4; ++m) { const float* xrow = xb + (size_t)EPI_ROWS(ai, m) * DM + c0;
; #pragma unroll
;                 for (int bj = 0; bj < 2; ++bj) { xv[m][bj][0] = __builtin_nontemporal_load((const f32x4*)(xrow + 32 * bj)); xv[m][bj][1] = __builtin_nontemporal_load((const f32x4*)(xrow + 32 * bj + 4)); } }
;     ...
;             for (int m = 0; m < 4; ++m) {
;                 const int r = EPI_ROWS(ai, m);
;                 float ss = 0.f;
; #pragma unroll
;                 for (int bj = 0; bj < 2; ++bj) {
;                     const f32x4 h0 = acc[ai][bj][m][0] + xv[m][bj][0], h1 = acc[ai][bj][m][1] + xv[m][bj][1];
;                     ss += (h0[0] * h0[0] + h0[1] * h0[1]) + (h0[2] * h0[2] + h0[3] * h0[3]) + (h1[0] * h1[0] + h1[1] * h1[1]) + (h1[2] * h1[2] + h1[3] * h1[3]);
;                     u32x4 w; w.x = cvt_pk_bf16(h0[0], h0[1]); w.y = cvt_pk_bf16(h0[2], h0[3]); w.z = cvt_pk_bf16(h1[0], h1[1]); w.w = cvt_pk_bf16(h1[2], h1[3]);
;                     *(u32x4*)(HP + (size_t)r * LDHP + c0 + 32 * bj) = w;
;                 }
;                 ss += __shfl_xor(ss, 16); ss += __shfl_xor(ss, 32);
;                 if (fq == 0) SS[(size_t)r * 16 + u.pn * 4 + wc] = ss;
;             }
.LBB0_908:
	s_or_b64 exec, exec, s[18:19]
	s_waitcnt vmcnt(8)
	v_pk_add_f32 v[80:81], v[80:81], v[152:153]
	v_pk_add_f32 v[78:79], v[78:79], v[150:151]
	s_waitcnt lgkmcnt(0)
	v_pk_add_f32 v[82:83], v[76:77], v[144:145]
	v_pk_add_f32 v[76:77], v[74:75], v[142:143]
	v_mul_f32_e32 v74, v79, v79
	v_mul_f32_e32 v75, v81, v81
	v_fmac_f32_e32 v74, v78, v78
	v_fmac_f32_e32 v75, v80, v80
	v_add_f32_e32 v74, v74, v75
	v_mul_f32_e32 v75, v77, v77
	v_fmac_f32_e32 v75, v76, v76
	v_add_f32_e32 v74, v74, v75
	v_mul_f32_e32 v75, v83, v83
	s_waitcnt vmcnt(6)
	v_pk_add_f32 v[72:73], v[72:73], v[136:137]
	v_pk_add_f32 v[70:71], v[70:71], v[134:135]
	v_fmac_f32_e32 v75, v82, v82
	v_cvt_pk_bf16_f32 v76, v76, v77
	v_cvt_pk_bf16_f32 v77, v82, v83
	v_pk_add_f32 v[82:83], v[66:67], v[130:131]
	v_mul_f32_e32 v66, v71, v71
	v_mul_f32_e32 v67, v73, v73
	v_fmac_f32_e32 v66, v70, v70
	v_fmac_f32_e32 v67, v72, v72
	v_add_f32_e32 v66, v66, v67
	v_mul_f32_e32 v67, v83, v83
	v_add_f32_e32 v84, v75, v74
	v_cvt_pk_bf16_f32 v75, v80, v81
	v_pk_add_f32 v[80:81], v[68:69], v[132:133]
	v_fmac_f32_e32 v67, v82, v82
	v_add_f32_e32 v66, v66, v67
	v_mul_f32_e32 v67, v81, v81
	v_fmac_f32_e32 v67, v80, v80
	v_add_f32_e32 v66, v67, v66
	v_add_f32_e32 v69, v84, v66
	s_nop 1
	v_mov_b32_e32 v84, v69
	s_nop 1
	v_permlane16_swap_b32_e32 v84, v69
	v_cvt_pk_bf16_f32 v74, v78, v79
	v_mov_b64_e32 v[78:79], s[82:83]
	v_mad_i64_i32 v[66:67], s[2:3], v210, s54, v[78:79]
	v_lshl_add_u64 v[78:79], v[204:205], 1, v[66:67]
	s_waitcnt lgkmcnt(0)
	v_add_f32_e32 v66, v69, v84
	s_nop 1
	v_mov_b32_e32 v67, v66
	s_nop 1
	v_permlane32_swap_b32_e32 v67, v66
	v_cvt_pk_bf16_f32 v68, v70, v71
	v_cvt_pk_bf16_f32 v69, v72, v73
	v_cvt_pk_bf16_f32 v70, v82, v83
	v_cvt_pk_bf16_f32 v71, v80, v81
	global_store_dwordx4 v[78:79], v[74:77], off
	global_store_dwordx4 v[78:79], v[68:71], off offset:64
	s_and_saveexec_b64 s[18:19], s[40:41]
	s_cbranch_execz .LBB0_910
	v_lshlrev_b64 v[68:69], 6, v[210:211]
	v_lshl_add_u64 v[68:69], s[8:9], 0, v[68:69]
	v_lshl_add_u64 v[68:69], s[66:67], 2, v[68:69]
	s_lshl_b32 s0, s30, 2
	v_lshl_add_u64 v[68:69], v[68:69], 0, s[0:1]
	s_waitcnt lgkmcnt(0)
	v_add_f32_e32 v66, v66, v67
	global_store_dword v[68:69], v66, off
.LBB0_910:
	s_or_b64 exec, exec, s[18:19]
	v_add_u32_e32 v124, 0x80, v208
	v_ashrrev_i32_e32 v125, 31, v124
	s_waitcnt lgkmcnt(0)
	v_lshlrev_b64 v[66:67], 12, v[124:125]
	v_lshl_add_u64 v[66:67], v[206:207], 0, v[66:67]
	global_load_dwordx4 v[126:129], v[66:67], off offset:16 nt
	global_load_dwordx4 v[130:133], v[66:67], off nt
	global_load_dwordx4 v[114:117], v[66:67], off offset:144 nt
	global_load_dwordx4 v[134:137], v[66:67], off offset:128 nt
	v_add_u32_e32 v122, 0x90, v208
	v_ashrrev_i32_e32 v123, 31, v122
	v_lshlrev_b64 v[66:67], 12, v[122:123]
	v_add_u32_e32 v120, 0xa0, v208
	v_lshl_add_u64 v[66:67], v[206:207], 0, v[66:67]
	v_ashrrev_i32_e32 v121, 31, v120
	global_load_dwordx4 v[106:109], v[66:67], off offset:16 nt
	global_load_dwordx4 v[110:113], v[66:67], off nt
	global_load_dwordx4 v[98:101], v[66:67], off offset:144 nt
	global_load_dwordx4 v[102:105], v[66:67], off offset:128 nt
	v_lshlrev_b64 v[66:67], 12, v[120:121]
	v_add_u32_e32 v118, 0xb0, v208
	v_lshl_add_u64 v[66:67], v[206:207], 0, v[66:67]
	v_ashrrev_i32_e32 v119, 31, v118
	global_load_dwordx4 v[90:93], v[66:67], off offset:16 nt
	global_load_dwordx4 v[94:97], v[66:67], off nt
	global_load_dwordx4 v[74:77], v[66:67], off offset:144 nt
	global_load_dwordx4 v[82:85], v[66:67], off offset:128 nt
	v_lshlrev_b64 v[66:67], 12, v[118:119]
	v_lshl_add_u64 v[70:71], v[206:207], 0, v[66:67]
	global_load_dwordx4 v[78:81], v[70:71], off offset:16 nt
	global_load_dwordx4 v[86:89], v[70:71], off nt
	global_load_dwordx4 v[66:69], v[70:71], off offset:144 nt
	s_nop 0
	global_load_dwordx4 v[70:73], v[70:71], off offset:128 nt
	s_waitcnt vmcnt(15)
	v_pk_add_f32 v[128:129], v[60:61], v[128:129]
	s_waitcnt vmcnt(14)
	v_pk_add_f32 v[64:65], v[64:65], v[132:133]
	v_pk_add_f32 v[62:63], v[62:63], v[130:131]
	v_pk_add_f32 v[60:61], v[58:59], v[126:127]
	v_mul_f32_e32 v58, v63, v63
	v_mul_f32_e32 v59, v65, v65
	v_fmac_f32_e32 v58, v62, v62
	v_fmac_f32_e32 v59, v64, v64
	v_add_f32_e32 v58, v58, v59
	v_mul_f32_e32 v59, v61, v61
	v_fmac_f32_e32 v59, v60, v60
	v_add_f32_e32 v58, v58, v59
	v_mul_f32_e32 v59, v129, v129
	v_fmac_f32_e32 v59, v128, v128
	v_add_f32_e32 v126, v59, v58
	v_cvt_pk_bf16_f32 v58, v62, v63
	v_mov_b64_e32 v[62:63], s[82:83]
	v_mad_i64_i32 v[62:63], s[2:3], v124, s54, v[62:63]
	v_cvt_pk_bf16_f32 v59, v64, v65
	v_cvt_pk_bf16_f32 v60, v60, v61
	v_cvt_pk_bf16_f32 v61, v128, v129
	v_lshl_add_u64 v[62:63], v[204:205], 1, v[62:63]
	s_waitcnt vmcnt(12)
	v_pk_add_f32 v[56:57], v[56:57], v[136:137]
	v_pk_add_f32 v[54:55], v[54:55], v[134:135]
	global_store_dwordx4 v[62:63], v[58:61], off
	s_nop 1
	v_pk_add_f32 v[58:59], v[52:53], v[116:117]
	v_pk_add_f32 v[52:53], v[50:51], v[114:115]
	v_mul_f32_e32 v50, v55, v55
	v_mul_f32_e32 v51, v57, v57
	v_fmac_f32_e32 v50, v54, v54
	v_fmac_f32_e32 v51, v56, v56
	v_add_f32_e32 v50, v50, v51
	v_mul_f32_e32 v51, v53, v53
	v_fmac_f32_e32 v51, v52, v52
	v_add_f32_e32 v50, v50, v51
	v_mul_f32_e32 v51, v59, v59
	v_fmac_f32_e32 v51, v58, v58
	v_add_f32_e32 v50, v51, v50
	v_add_f32_e32 v60, v126, v50
	v_cvt_pk_bf16_f32 v50, v54, v55
	v_cvt_pk_bf16_f32 v51, v56, v57
	v_cvt_pk_bf16_f32 v52, v52, v53
	v_cvt_pk_bf16_f32 v53, v58, v59
	global_store_dwordx4 v[62:63], v[50:53], off offset:64
	s_nop 1
	v_mov_b32_e32 v50, v60
	s_nop 1
	v_permlane16_swap_b32_e32 v50, v60
	s_waitcnt lgkmcnt(0)
	v_add_f32_e32 v50, v60, v50
	s_nop 1
	v_mov_b32_e32 v51, v50
	s_nop 1
	v_permlane32_swap_b32_e32 v51, v50
	s_and_saveexec_b64 s[18:19], s[40:41]
	s_cbranch_execz .LBB0_912
	v_lshlrev_b64 v[52:53], 6, v[124:125]
	v_lshl_add_u64 v[52:53], s[8:9], 0, v[52:53]
	v_lshl_add_u64 v[52:53], s[66:67], 2, v[52:53]
	s_lshl_b32 s0, s30, 2
	v_lshl_add_u64 v[52:53], v[52:53], 0, s[0:1]
	s_waitcnt lgkmcnt(0)
	v_add_f32_e32 v50, v50, v51
	global_store_dword v[52:53], v50, off
; __device__ __forceinline__ unsigned cvt_pk_bf16(float lo, float hi) { const f32x2_t v = {lo, hi}; const bf16x2_t b = __builtin_convertvector(v, bf16x2_t); return __builtin_bit_cast(unsigned, b); }
;     __device__ __forceinline__ void operator()(f32x4 (&acc)[2][2][4][2], const Unit& u, int wr, int wc, int fr, int fq) const {
;     ...
;             for (int m = 0; m < 4; ++m) {
;                 const int r = EPI_ROWS(ai, m);
;                 float ss = 0.f;
; #pragma unroll
;                 for (int bj = 0; bj < 2; ++bj) {
;                     const f32x4 h0 = acc[ai][bj][m][0] + xv[m][bj][0], h1 = acc[ai][bj][m][1] + xv[m][bj][1];
;                     ss += (h0[0] * h0[0] + h0[1] * h0[1]) + (h0[2] * h0[2] + h0[3] * h0[3]) + (h1[0] * h1[0] + h1[1] * h1[1]) + (h1[2] * h1[2] + h1[3] * h1[3]);
;                     u32x4 w; w.x = cvt_pk_bf16(h0[0], h0[1]); w.y = cvt_pk_bf16(h0[2], h0[3]); w.z = cvt_pk_bf16(h1[0], h1[1]); w.w = cvt_pk_bf16(h1[2], h1[3]);
;                     *(u32x4*)(HP + (size_t)r * LDHP + c0 + 32 * bj) = w;
;                 }
;                 ss += __shfl_xor(ss, 16); ss += __shfl_xor(ss, 32);
;                 if (fq == 0) SS[(size_t)r * 16 + u.pn * 4 + wc] = ss;
;             }
.LBB0_912:
	s_or_b64 exec, exec, s[18:19]
	s_waitcnt vmcnt(12)
	v_pk_add_f32 v[48:49], v[48:49], v[112:113]
	v_pk_add_f32 v[46:47], v[46:47], v[110:111]
	s_waitcnt lgkmcnt(0)
	v_pk_add_f32 v[50:51], v[44:45], v[108:109]
	v_pk_add_f32 v[44:45], v[42:43], v[106:107]
	v_mul_f32_e32 v42, v47, v47
	v_mul_f32_e32 v43, v49, v49
	v_fmac_f32_e32 v42, v46, v46
	v_fmac_f32_e32 v43, v48, v48
	v_add_f32_e32 v42, v42, v43
	v_mul_f32_e32 v43, v45, v45
	v_fmac_f32_e32 v43, v44, v44
	v_add_f32_e32 v42, v42, v43
	v_mul_f32_e32 v43, v51, v51
	s_waitcnt vmcnt(10)
	v_pk_add_f32 v[40:41], v[40:41], v[104:105]
	v_pk_add_f32 v[38:39], v[38:39], v[102:103]
	v_fmac_f32_e32 v43, v50, v50
	v_cvt_pk_bf16_f32 v44, v44, v45
	v_cvt_pk_bf16_f32 v45, v50, v51
	v_pk_add_f32 v[50:51], v[34:35], v[98:99]
	v_mul_f32_e32 v34, v39, v39
	v_mul_f32_e32 v35, v41, v41
	v_fmac_f32_e32 v34, v38, v38
	v_fmac_f32_e32 v35, v40, v40
	v_add_f32_e32 v34, v34, v35
	v_mul_f32_e32 v35, v51, v51
	v_add_f32_e32 v52, v43, v42
	v_cvt_pk_bf16_f32 v43, v48, v49
	v_pk_add_f32 v[48:49], v[36:37], v[100:101]
	v_fmac_f32_e32 v35, v50, v50
	v_add_f32_e32 v34, v34, v35
	v_mul_f32_e32 v35, v49, v49
	v_fmac_f32_e32 v35, v48, v48
	v_add_f32_e32 v34, v35, v34
	v_add_f32_e32 v37, v52, v34
	s_nop 1
	v_mov_b32_e32 v52, v37
	s_nop 1
	v_permlane16_swap_b32_e32 v52, v37
	v_cvt_pk_bf16_f32 v42, v46, v47
	v_mov_b64_e32 v[46:47], s[82:83]
	v_mad_i64_i32 v[34:35], s[2:3], v122, s54, v[46:47]
	v_lshl_add_u64 v[46:47], v[204:205], 1, v[34:35]
	s_waitcnt lgkmcnt(0)
	v_add_f32_e32 v34, v37, v52
	s_nop 1
	v_mov_b32_e32 v35, v34
	s_nop 1
	v_permlane32_swap_b32_e32 v35, v34
	v_cvt_pk_bf16_f32 v36, v38, v39
	v_cvt_pk_bf16_f32 v37, v40, v41
	v_cvt_pk_bf16_f32 v38, v50, v51
	v_cvt_pk_bf16_f32 v39, v48, v49
	global_store_dwordx4 v[46:47], v[42:45], off
	global_store_dwordx4 v[46:47], v[36:39], off offset:64
	s_and_saveexec_b64 s[18:19], s[40:41]
	s_cbranch_execz .LBB0_914
	v_lshlrev_b64 v[36:37], 6, v[122:123]
	v_lshl_add_u64 v[36:37], s[8:9], 0, v[36:37]
	v_lshl_add_u64 v[36:37], s[66:67], 2, v[36:37]
	s_lshl_b32 s0, s30, 2
	v_lshl_add_u64 v[36:37], v[36:37], 0, s[0:1]
	s_waitcnt lgkmcnt(0)
	v_add_f32_e32 v34, v34, v35
	global_store_dword v[36:37], v34, off
.LBB0_914:
	s_or_b64 exec, exec, s[18:19]
	s_waitcnt vmcnt(10)
	v_pk_add_f32 v[32:33], v[32:33], v[96:97]
	v_pk_add_f32 v[30:31], v[30:31], v[94:95]
	s_waitcnt lgkmcnt(0)
	v_pk_add_f32 v[34:35], v[28:29], v[92:93]
	v_pk_add_f32 v[28:29], v[26:27], v[90:91]
	v_mul_f32_e32 v26, v31, v31
	v_mul_f32_e32 v27, v33, v33
	v_fmac_f32_e32 v26, v30, v30
	v_fmac_f32_e32 v27, v32, v32
	v_add_f32_e32 v26, v26, v27
	v_mul_f32_e32 v27, v29, v29
	v_fmac_f32_e32 v27, v28, v28
	v_add_f32_e32 v26, v26, v27
	v_mul_f32_e32 v27, v35, v35
	s_waitcnt vmcnt(8)
	v_pk_add_f32 v[24:25], v[24:25], v[84:85]
	v_pk_add_f32 v[22:23], v[22:23], v[82:83]
	v_fmac_f32_e32 v27, v34, v34
	v_cvt_pk_bf16_f32 v28, v28, v29
	v_cvt_pk_bf16_f32 v29, v34, v35
	v_pk_add_f32 v[34:35], v[18:19], v[74:75]
	v_mul_f32_e32 v18, v23, v23
	v_mul_f32_e32 v19, v25, v25
	v_fmac_f32_e32 v18, v22, v22
	v_fmac_f32_e32 v19, v24, v24
	v_add_f32_e32 v18, v18, v19
	v_mul_f32_e32 v19, v35, v35
	v_add_f32_e32 v36, v27, v26
	v_cvt_pk_bf16_f32 v27, v32, v33
	v_pk_add_f32 v[32:33], v[20:21], v[76:77]
	v_fmac_f32_e32 v19, v34, v34
	v_add_f32_e32 v18, v18, v19
	v_mul_f32_e32 v19, v33, v33
	v_fmac_f32_e32 v19, v32, v32
	v_add_f32_e32 v18, v19, v18
	v_add_f32_e32 v21, v36, v18
	s_nop 1
	v_mov_b32_e32 v36, v21
	s_nop 1
	v_permlane16_swap_b32_e32 v36, v21
	v_cvt_pk_bf16_f32 v26, v30, v31
	v_mov_b64_e32 v[30:31], s[82:83]
	v_mad_i64_i32 v[18:19], s[2:3], v120, s54, v[30:31]
	v_lshl_add_u64 v[30:31], v[204:205], 1, v[18:19]
	s_waitcnt lgkmcnt(0)
	v_add_f32_e32 v18, v21, v36
	s_nop 1
	v_mov_b32_e32 v19, v18
	s_nop 1
	v_permlane32_swap_b32_e32 v19, v18
	v_cvt_pk_bf16_f32 v20, v22, v23
	v_cvt_pk_bf16_f32 v21, v24, v25
	v_cvt_pk_bf16_f32 v22, v34, v35
	v_cvt_pk_bf16_f32 v23, v32, v33
	global_store_dwordx4 v[30:31], v[26:29], off
	global_store_dwordx4 v[30:31], v[20:23], off offset:64
	s_and_saveexec_b64 s[18:19], s[40:41]
	s_cbranch_execz .LBB0_916
	v_lshlrev_b64 v[20:21], 6, v[120:121]
	v_lshl_add_u64 v[20:21], s[8:9], 0, v[20:21]
	v_lshl_add_u64 v[20:21], s[66:67], 2, v[20:21]
	s_lshl_b32 s0, s30, 2
	v_lshl_add_u64 v[20:21], v[20:21], 0, s[0:1]
	s_waitcnt lgkmcnt(0)
	v_add_f32_e32 v18, v18, v19
	global_store_dword v[20:21], v18, off
.LBB0_916:
	s_or_b64 exec, exec, s[18:19]
	s_waitcnt vmcnt(8)
	v_pk_add_f32 v[16:17], v[16:17], v[88:89]
	v_pk_add_f32 v[14:15], v[14:15], v[86:87]
	s_waitcnt lgkmcnt(0)
	v_pk_add_f32 v[18:19], v[12:13], v[80:81]
	v_pk_add_f32 v[12:13], v[10:11], v[78:79]
	v_mul_f32_e32 v10, v15, v15
	v_mul_f32_e32 v11, v17, v17
	v_fmac_f32_e32 v10, v14, v14
	v_fmac_f32_e32 v11, v16, v16
	v_add_f32_e32 v10, v10, v11
	v_mul_f32_e32 v11, v13, v13
	v_fmac_f32_e32 v11, v12, v12
	v_add_f32_e32 v10, v10, v11
	v_mul_f32_e32 v11, v19, v19
	s_waitcnt vmcnt(6)
	v_pk_add_f32 v[8:9], v[8:9], v[72:73]
	v_pk_add_f32 v[6:7], v[6:7], v[70:71]
	v_fmac_f32_e32 v11, v18, v18
	v_cvt_pk_bf16_f32 v12, v12, v13
	v_cvt_pk_bf16_f32 v13, v18, v19
	v_pk_add_f32 v[18:19], v[2:3], v[66:67]
	v_mul_f32_e32 v2, v7, v7
	v_mul_f32_e32 v3, v9, v9
	v_fmac_f32_e32 v2, v6, v6
	v_fmac_f32_e32 v3, v8, v8
	v_add_f32_e32 v2, v2, v3
	v_mul_f32_e32 v3, v19, v19
	v_add_f32_e32 v20, v11, v10
	v_cvt_pk_bf16_f32 v11, v16, v17
	v_pk_add_f32 v[16:17], v[4:5], v[68:69]
	v_fmac_f32_e32 v3, v18, v18
	v_add_f32_e32 v2, v2, v3
	v_mul_f32_e32 v3, v17, v17
	v_fmac_f32_e32 v3, v16, v16
	v_add_f32_e32 v2, v3, v2
	v_add_f32_e32 v5, v20, v2
	s_nop 1
	v_mov_b32_e32 v20, v5
	s_nop 1
	v_permlane16_swap_b32_e32 v20, v5
	v_cvt_pk_bf16_f32 v10, v14, v15
	v_mov_b64_e32 v[14:15], s[82:83]
	v_mad_i64_i32 v[2:3], s[2:3], v118, s54, v[14:15]
	v_lshl_add_u64 v[14:15], v[204:205], 1, v[2:3]
	s_waitcnt lgkmcnt(0)
	v_add_f32_e32 v2, v5, v20
	s_nop 1
	v_mov_b32_e32 v3, v2
	s_nop 1
	v_permlane32_swap_b32_e32 v3, v2
	v_cvt_pk_bf16_f32 v4, v6, v7
	v_cvt_pk_bf16_f32 v5, v8, v9
	v_cvt_pk_bf16_f32 v6, v18, v19
	v_cvt_pk_bf16_f32 v7, v16, v17
	global_store_dwordx4 v[14:15], v[10:13], off
	global_store_dwordx4 v[14:15], v[4:7], off offset:64
	s_and_saveexec_b64 s[18:19], s[40:41]
	s_cbranch_execz .LBB0_918
	v_lshlrev_b64 v[4:5], 6, v[118:119]
	v_lshl_add_u64 v[4:5], s[8:9], 0, v[4:5]
	v_lshl_add_u64 v[4:5], s[66:67], 2, v[4:5]
	s_lshl_b32 s0, s30, 2
	v_lshl_add_u64 v[4:5], v[4:5], 0, s[0:1]
	s_waitcnt lgkmcnt(0)
	v_add_f32_e32 v2, v2, v3
	global_store_dword v[4:5], v2, off
